# nt hint on the mixer elementwise (P2) output stores, on top of v18
# baseline (speedup 1.0000x reference)
.LBB0_240:
	s_or_b64 exec, exec, s[4:5]
	v_mov_b32_e32 v75, v99
	s_waitcnt lgkmcnt(0)
	v_lshl_add_u64 v[40:41], s[14:15], 0, v[74:75]
	s_mov_b64 s[4:5], 0x1000
	v_add_co_u32_e32 v44, vcc, s33, v40
	v_lshlrev_b32_e32 v104, 16, v8
	v_lshlrev_b32_e32 v105, 16, v12
	v_and_b32_e32 v103, 0xffff0000, v12
	v_and_b32_e32 v102, 0xffff0000, v8
	v_lshlrev_b32_e32 v100, 16, v9
	v_lshlrev_b32_e32 v101, 16, v13
	v_and_b32_e32 v97, 0xffff0000, v13
	v_and_b32_e32 v96, 0xffff0000, v9
	v_lshlrev_b32_e32 v94, 16, v10
	v_lshlrev_b32_e32 v95, 16, v14
	v_and_b32_e32 v93, 0xffff0000, v14
	v_and_b32_e32 v92, 0xffff0000, v10
	v_lshlrev_b32_e32 v90, 16, v11
	v_lshlrev_b32_e32 v91, 16, v15
	v_and_b32_e32 v89, 0xffff0000, v15
	v_and_b32_e32 v88, 0xffff0000, v11
	v_lshlrev_b32_e32 v83, 16, v36
	v_lshlrev_b32_e32 v82, 16, v32
	v_and_b32_e32 v9, 0xffff0000, v36
	v_and_b32_e32 v8, 0xffff0000, v32
	v_lshlrev_b32_e32 v85, 16, v37
	v_lshlrev_b32_e32 v84, 16, v33
	v_and_b32_e32 v11, 0xffff0000, v37
	v_and_b32_e32 v10, 0xffff0000, v33
	v_lshlrev_b32_e32 v79, 16, v38
	v_lshlrev_b32_e32 v78, 16, v34
	v_and_b32_e32 v13, 0xffff0000, v38
	v_and_b32_e32 v12, 0xffff0000, v34
	v_lshlrev_b32_e32 v81, 16, v39
	v_lshlrev_b32_e32 v80, 16, v35
	v_and_b32_e32 v15, 0xffff0000, v39
	v_and_b32_e32 v14, 0xffff0000, v35
	global_load_dwordx4 v[32:35], v74, s[14:15] offset:16
	global_load_dwordx4 v[36:39], v74, s[14:15]
	v_lshl_add_u64 v[42:43], v[40:41], 0, s[4:5]
	v_addc_co_u32_e32 v45, vcc, 0, v41, vcc
	v_lshl_add_u64 v[46:47], v[40:41], 0, s[74:75]
	global_load_dwordx4 v[56:59], v[44:45], off offset:-4096
	global_load_dwordx4 v[48:51], v[42:43], off offset:16
	s_nop 0
	global_load_dwordx4 v[40:43], v[44:45], off
	s_nop 0
	global_load_dwordx4 v[44:47], v[46:47], off offset:16
	v_lshl_add_u64 v[106:107], s[12:13], 0, v[98:99]
	v_lshlrev_b32_e32 v98, 16, v52
	v_and_b32_e32 v110, 0xffff0000, v52
	v_lshlrev_b32_e32 v112, 16, v53
	v_and_b32_e32 v113, 0xffff0000, v53
	v_lshlrev_b32_e32 v114, 16, v54
	v_and_b32_e32 v115, 0xffff0000, v54
	v_lshlrev_b32_e32 v116, 16, v55
	v_and_b32_e32 v118, 0xffff0000, v55
	s_waitcnt vmcnt(8)
	v_mov_b32_e32 v54, v60
	v_mov_b32_e32 v55, v104
	v_pk_mov_b32 v[60:61], v[60:61], v[102:103] op_sel:[1,0]
	v_mov_b32_e32 v111, v100
	v_lshl_add_u64 v[86:87], v[106:107], 0, v[86:87]
	v_cmp_eq_u32_e32 vcc, v108, v109
	s_waitcnt vmcnt(4)
	v_mov_b32_e32 v52, v36
	s_waitcnt vmcnt(1)
	v_mov_b32_e32 v53, v40
	v_pk_mul_f32 v[54:55], v[54:55], v[52:53]
	s_waitcnt vmcnt(0)
	v_mov_b32_e32 v117, v47
	v_fma_f32 v54, v24, v56, v54
	v_add_f32_e32 v54, v54, v55
	v_mul_f32_e32 v98, v54, v98
	v_mov_b32_e32 v54, v37
	v_mov_b32_e32 v55, v41
	v_pk_mul_f32 v[60:61], v[60:61], v[54:55]
	s_nop 0
	v_fma_f32 v60, v25, v57, v60
	v_add_f32_e32 v60, v60, v61
	v_mul_f32_e32 v119, v60, v110
	v_mov_b32_e32 v110, v62
	v_mov_b32_e32 v60, v38
	v_mov_b32_e32 v61, v42
	v_pk_mul_f32 v[110:111], v[110:111], v[60:61]
	s_nop 0
	v_fma_f32 v110, v26, v58, v110
	v_add_f32_e32 v110, v110, v111
	v_mul_f32_e32 v120, v110, v112
	v_pk_mov_b32 v[110:111], v[62:63], v[96:97] op_sel:[1,0]
	v_mov_b32_e32 v62, v39
	v_mov_b32_e32 v63, v43
	v_pk_mul_f32 v[110:111], v[110:111], v[62:63]
	v_mov_b32_e32 v112, v32
	v_fma_f32 v110, v27, v59, v110
	v_add_f32_e32 v110, v110, v111
	v_mul_f32_e32 v121, v110, v113
	v_mov_b32_e32 v110, v28
	v_mov_b32_e32 v111, v94
	v_mov_b32_e32 v113, v44
	v_pk_mul_f32 v[110:111], v[110:111], v[112:113]
	v_pk_mov_b32 v[28:29], v[28:29], v[92:93] op_sel:[1,0]
	v_fma_f32 v110, v20, v48, v110
	v_add_f32_e32 v110, v110, v111
	v_mul_f32_e32 v122, v110, v114
	v_mov_b32_e32 v110, v33
	v_mov_b32_e32 v111, v45
	v_pk_mul_f32 v[28:29], v[28:29], v[110:111]
	v_mov_b32_e32 v114, v34
	v_fma_f32 v28, v21, v49, v28
	v_add_f32_e32 v28, v28, v29
	v_mul_f32_e32 v123, v28, v115
	v_mov_b32_e32 v28, v30
	v_mov_b32_e32 v29, v90
	v_mov_b32_e32 v115, v46
	v_pk_mul_f32 v[28:29], v[28:29], v[114:115]
	s_nop 0
	v_fma_f32 v28, v22, v50, v28
	v_add_f32_e32 v28, v28, v29
	v_mul_f32_e32 v124, v28, v116
	v_pk_mov_b32 v[28:29], v[30:31], v[88:89] op_sel:[1,0]
	v_mov_b32_e32 v116, v35
	v_pk_mul_f32 v[28:29], v[28:29], v[116:117]
	s_nop 0
	v_fma_f32 v28, v23, v51, v28
	v_add_f32_e32 v28, v28, v29
	v_mul_f32_e32 v31, v28, v118
	v_cvt_pk_bf16_f32 v28, v98, v119
	v_cvt_pk_bf16_f32 v29, v120, v121
	v_cvt_pk_bf16_f32 v30, v122, v123
	v_cvt_pk_bf16_f32 v31, v124, v31
	global_store_dwordx4 v[86:87], v[28:31], off nt
	v_lshlrev_b32_e32 v86, 16, v17
	v_and_b32_e32 v87, 0xffff0000, v17
	v_mov_b32_e32 v28, v56
	v_mov_b32_e32 v29, v40
	v_lshlrev_b32_e32 v30, 16, v16
	v_and_b32_e32 v31, 0xffff0000, v16
	v_pk_mul_f32 v[16:17], v[28:29], v[104:105]
	v_mov_b32_e32 v40, v57
	v_fma_f32 v16, v24, v36, v16
	v_add_f32_e32 v16, v16, v17
	v_mul_f32_e32 v30, v16, v30
	v_pk_mul_f32 v[16:17], v[40:41], v[102:103]
	v_mov_b32_e32 v24, v58
	v_fma_f32 v16, v25, v37, v16
	v_add_f32_e32 v16, v16, v17
	v_mov_b32_e32 v25, v42
	v_mul_f32_e32 v31, v16, v31
	v_pk_mul_f32 v[16:17], v[24:25], v[100:101]
	v_mov_b32_e32 v42, v59
	v_fma_f32 v16, v26, v38, v16
	v_add_f32_e32 v16, v16, v17
	v_mul_f32_e32 v86, v16, v86
	v_pk_mul_f32 v[16:17], v[42:43], v[96:97]
	v_mov_b32_e32 v26, v48
	v_fma_f32 v16, v27, v39, v16
	v_add_f32_e32 v16, v16, v17
	v_mov_b32_e32 v27, v44
	v_mul_f32_e32 v87, v16, v87
	v_pk_mul_f32 v[16:17], v[26:27], v[94:95]
	v_lshlrev_b32_e32 v98, 16, v18
	v_fma_f32 v16, v20, v32, v16
	v_add_f32_e32 v16, v16, v17
	v_mov_b32_e32 v44, v49
	v_mul_f32_e32 v98, v16, v98
	v_pk_mul_f32 v[16:17], v[44:45], v[92:93]
	v_and_b32_e32 v18, 0xffff0000, v18
	v_fma_f32 v16, v21, v33, v16
	v_add_f32_e32 v16, v16, v17
	v_mov_b32_e32 v20, v50
	v_mov_b32_e32 v21, v46
	v_mul_f32_e32 v18, v16, v18
	v_pk_mul_f32 v[16:17], v[20:21], v[90:91]
	v_lshlrev_b32_e32 v118, 16, v19
	v_fma_f32 v16, v22, v34, v16
	v_add_f32_e32 v16, v16, v17
	v_mov_b32_e32 v46, v51
	v_mul_f32_e32 v22, v16, v118
	v_pk_mul_f32 v[16:17], v[46:47], v[88:89]
	v_and_b32_e32 v19, 0xffff0000, v19
	v_fma_f32 v16, v23, v35, v16
	v_add_f32_e32 v16, v16, v17
	v_mul_f32_e32 v19, v16, v19
	v_cvt_pk_bf16_f32 v16, v30, v31
	v_cvt_pk_bf16_f32 v17, v86, v87
	v_cvt_pk_bf16_f32 v18, v98, v18
	v_cvt_pk_bf16_f32 v19, v22, v19
	v_lshl_add_u64 v[22:23], v[106:107], 0, v[76:77]
	global_store_dwordx4 v[22:23], v[16:19], off nt
	v_lshlrev_b32_e32 v22, 16, v6
	v_and_b32_e32 v6, 0xffff0000, v6
	v_lshlrev_b32_e32 v16, 16, v4
	v_and_b32_e32 v17, 0xffff0000, v4
	v_lshlrev_b32_e32 v18, 16, v5
	v_and_b32_e32 v19, 0xffff0000, v5
	v_mov_b32_e32 v4, v104
	v_mov_b32_e32 v5, v82
	v_pk_mul_f32 v[4:5], v[52:53], v[4:5]
	v_lshlrev_b32_e32 v23, 16, v7
	v_fma_f32 v4, v56, v105, v4
	v_add_f32_e32 v4, v4, v5
	v_mul_f32_e32 v16, v4, v16
	v_mov_b32_e32 v4, v102
	v_mov_b32_e32 v5, v8
	v_pk_mul_f32 v[4:5], v[54:55], v[4:5]
	v_and_b32_e32 v7, 0xffff0000, v7
	v_fma_f32 v4, v57, v103, v4
	v_add_f32_e32 v4, v4, v5
	v_mul_f32_e32 v17, v4, v17
	v_mov_b32_e32 v4, v100
	v_mov_b32_e32 v5, v84
	v_pk_mul_f32 v[4:5], v[60:61], v[4:5]
	s_nop 0
	v_fma_f32 v4, v58, v101, v4
	v_add_f32_e32 v4, v4, v5
	v_mul_f32_e32 v18, v4, v18
	v_mov_b32_e32 v4, v96
	v_mov_b32_e32 v5, v10
	v_pk_mul_f32 v[4:5], v[62:63], v[4:5]
	s_nop 0
	v_fma_f32 v4, v59, v97, v4
	v_add_f32_e32 v4, v4, v5
	v_mul_f32_e32 v19, v4, v19
	v_mov_b32_e32 v4, v94
	v_mov_b32_e32 v5, v78
	v_pk_mul_f32 v[4:5], v[112:113], v[4:5]
	s_nop 0
	v_fma_f32 v4, v48, v95, v4
	v_add_f32_e32 v4, v4, v5
	v_mul_f32_e32 v22, v4, v22
	v_mov_b32_e32 v4, v92
	v_mov_b32_e32 v5, v12
	v_pk_mul_f32 v[4:5], v[110:111], v[4:5]
	s_nop 0
	v_fma_f32 v4, v49, v93, v4
	v_add_f32_e32 v4, v4, v5
	v_mul_f32_e32 v6, v4, v6
	v_mov_b32_e32 v4, v90
	v_mov_b32_e32 v5, v80
	v_pk_mul_f32 v[4:5], v[114:115], v[4:5]
	s_nop 0
	v_fma_f32 v4, v50, v91, v4
	v_add_f32_e32 v4, v4, v5
	v_mul_f32_e32 v23, v4, v23
	v_mov_b32_e32 v4, v88
	v_mov_b32_e32 v5, v14
	v_pk_mul_f32 v[4:5], v[116:117], v[4:5]
	s_nop 0
	v_fma_f32 v4, v51, v89, v4
	v_add_f32_e32 v4, v4, v5
	v_mul_f32_e32 v7, v4, v7
	v_cvt_pk_bf16_f32 v4, v16, v17
	v_cvt_pk_bf16_f32 v5, v18, v19
	v_cvt_pk_bf16_f32 v6, v22, v6
	v_cvt_pk_bf16_f32 v7, v23, v7
	v_lshl_add_u64 v[16:17], v[106:107], 0, v[72:73]
	global_store_dwordx4 v[16:17], v[4:7], off nt
	v_lshlrev_b32_e32 v16, 16, v2
	v_and_b32_e32 v2, 0xffff0000, v2
	v_lshlrev_b32_e32 v4, 16, v0
	v_and_b32_e32 v5, 0xffff0000, v0
	v_lshlrev_b32_e32 v6, 16, v1
	v_and_b32_e32 v7, 0xffff0000, v1
	v_pk_mul_f32 v[0:1], v[28:29], v[82:83]
	v_lshlrev_b32_e32 v17, 16, v3
	v_fma_f32 v0, v36, v105, v0
	v_add_f32_e32 v0, v0, v1
	v_mul_f32_e32 v4, v0, v4
	v_pk_mul_f32 v[0:1], v[40:41], v[8:9]
	v_and_b32_e32 v3, 0xffff0000, v3
	v_fma_f32 v0, v37, v103, v0
	v_add_f32_e32 v0, v0, v1
	v_mul_f32_e32 v5, v0, v5
	v_pk_mul_f32 v[0:1], v[24:25], v[84:85]
	s_nop 0
	v_fma_f32 v0, v38, v101, v0
	v_add_f32_e32 v0, v0, v1
	v_mul_f32_e32 v6, v0, v6
	v_pk_mul_f32 v[0:1], v[42:43], v[10:11]
	s_nop 0
	v_fma_f32 v0, v39, v97, v0
	v_add_f32_e32 v0, v0, v1
	v_mul_f32_e32 v7, v0, v7
	v_pk_mul_f32 v[0:1], v[26:27], v[78:79]
	s_nop 0
	v_fma_f32 v0, v32, v95, v0
	v_add_f32_e32 v0, v0, v1
	v_mul_f32_e32 v16, v0, v16
	v_pk_mul_f32 v[0:1], v[44:45], v[12:13]
	s_nop 0
	v_fma_f32 v0, v33, v93, v0
	v_add_f32_e32 v0, v0, v1
	v_mul_f32_e32 v2, v0, v2
	v_pk_mul_f32 v[0:1], v[20:21], v[80:81]
	s_nop 0
	v_fma_f32 v0, v34, v91, v0
	v_add_f32_e32 v0, v0, v1
	v_mul_f32_e32 v17, v0, v17
	v_pk_mul_f32 v[0:1], v[46:47], v[14:15]
	s_nop 0
	v_fma_f32 v0, v35, v89, v0
	v_add_f32_e32 v0, v0, v1
	v_mul_f32_e32 v3, v0, v3
	v_cvt_pk_bf16_f32 v0, v4, v5
	v_lshl_add_u64 v[4:5], v[106:107], 0, v[70:71]
	v_cvt_pk_bf16_f32 v1, v6, v7
	v_cvt_pk_bf16_f32 v2, v16, v2
	v_cvt_pk_bf16_f32 v3, v17, v3
	global_store_dwordx4 v[4:5], v[0:3], off nt
	s_and_saveexec_b64 s[4:5], vcc
	s_cbranch_execz .LBB0_231
	s_load_dwordx2 s[22:23], s[76:77], 0xb0
	v_cndmask_b32_e64 v98, v216, v217, s[2:3]
	v_lshlrev_b64 v[2:3], 13, v[68:69]
	s_waitcnt lgkmcnt(0)
	v_lshl_add_u64 v[0:1], s[22:23], 0, v[98:99]
	v_lshl_add_u64 v[0:1], v[0:1], 0, v[2:3]
	v_lshl_add_u64 v[4:5], v[0:1], 0, v[74:75]
	v_mov_b32_e32 v0, v82
	v_mov_b32_e32 v1, v8
	v_mov_b32_e32 v2, v84
	v_mov_b32_e32 v3, v10
	global_store_dwordx4 v[4:5], v[0:3], off
	v_mov_b32_e32 v8, v83
	v_mov_b32_e32 v10, v85
	v_mov_b32_e32 v0, v78
	v_mov_b32_e32 v1, v12
	v_mov_b32_e32 v2, v80
	v_mov_b32_e32 v3, v14
	global_store_dwordx4 v[4:5], v[0:3], off offset:16
	v_mov_b32_e32 v12, v79
	v_mov_b32_e32 v14, v81
	v_add_co_u32_e32 v0, vcc, 0x1000, v4
	s_nop 1
	v_addc_co_u32_e32 v1, vcc, 0, v5, vcc
	global_store_dwordx4 v[0:1], v[8:11], off
	global_store_dwordx4 v[0:1], v[12:15], off offset:16
	s_branch .LBB0_231
